# grid barriers 2-6: XCD-local release (no L2 write-back, no cross-XCD rendezvous) when every blockIdx%8 class sits on one XCD (run-time check), else unchanged two-level barrier
# speedup vs baseline: 1.0497x; 1.0289x over previous
; #define LAS __attribute__((address_space(3)))
; __device__ __forceinline__ unsigned xb_add(unsigned* p, unsigned v) { return __hip_atomic_fetch_add(p, v, __ATOMIC_RELAXED, __HIP_MEMORY_SCOPE_AGENT); }
; __device__ __forceinline__ unsigned xb_xcc_id() { return (unsigned)__builtin_amdgcn_s_getreg((3 << 11) | 20) & 0xFu; }
; __device__ __forceinline__ XcdBarrier xcd_barrier_post(unsigned* bar, volatile LAS unsigned* st) {
;     XcdBarrier b; b.bar = bar; b.x = xb_xcc_id(); b.st = st;
;     if (threadIdx.x == 0) (void)xb_add(&bar[XB_XCNT(b.x)], 1u);
;     return b;
; }
; __global__ void __launch_bounds__(NTHREADS) fwd_megakernel(Params P) {
;     ...
;     volatile LAS unsigned* xb_st = (volatile LAS unsigned*)(lds + LDS_BYTES - 16);
;     if (threadIdx.x == 0) { xb_st[0] = 0u; xb_st[1] = 0u; }
;     __syncthreads();
;     const XcdBarrier xbar = xcd_barrier_post((unsigned*)(ws + WS_BAR), xb_st);
.LBB0_2:
	s_or_b64 exec, exec, s[4:5]
	s_load_dwordx16 s[52:67], s[0:1], 0x0
	s_waitcnt lgkmcnt(0)
	s_barrier
	s_add_u32 s30, s50, 0x1180000
	s_getreg_b32 s0, hwreg(HW_REG_XCC_ID, 0, 4)
	s_addc_u32 s31, s51, 0
	s_and_b32 s33, s0, 15
	s_mov_b64 s[0:1], exec
	v_readlane_b32 s4, v255, 3
	v_readlane_b32 s5, v255, 4
	s_and_b64 s[4:5], s[0:1], s[4:5]
	s_mov_b64 exec, s[4:5]
	s_cbranch_execz .LBB0_5
	s_mov_b64 s[4:5], exec
	v_mbcnt_lo_u32_b32 v1, s4, 0
	v_mbcnt_hi_u32_b32 v1, s5, v1
	v_cmp_eq_u32_e32 vcc, 0, v1
	s_and_b64 s[6:7], exec, vcc
	s_mov_b64 exec, s[6:7]
	s_cbranch_execz .LBB0_5
	s_lshl_b32 s2, s33, 8
	s_bcnt1_i32_b64 s4, s[4:5]
	v_mov_b32_e32 v1, s2
	v_mov_b32_e32 v2, s4
	global_atomic_add v1, v2, s[30:31] offset:1024
	s_and_b32 s2, s3, 7
	s_lshl_b32 s2, s2, 2
	s_lshl_b32 vcc_lo, 1, s33
	v_mov_b32_e32 v1, s2
	v_mov_b32_e32 v2, vcc_lo
	global_atomic_or v1, v2, s[30:31]

;     __host__ __device__ bool next(int i, Unit& u) const {
;         const long L = (long)i * G + c; if (L >= nwg) return false;
;         int wgid = (int)L; { const int q = nwg / NXCD, r = nwg % NXCD, xcd = wgid % NXCD, off = wgid / NXCD; wgid = (xcd < r ? xcd * (q + 1) : r * (q + 1) + (xcd - r) * q) + off; }
;         const int nig = WGM * nN, gid = wgid / nig, fm = gid * WGM, gsz = (nM - fm) < WGM ? (nM - fm) : WGM;
;         u.pm = fm + ((wgid % nig) % gsz); u.pn = (wgid % nig) / gsz; return true;
; __global__ void __launch_bounds__(NTHREADS) fwd_megakernel(Params P) {
;     ...
;     xcd_barrier(xbar);
;     if constexpr ((PH_MASK & 2) != 0) {
;         pg8::Gemm g{(const bf16_t*)(ws + WS_XB), (const bf16_t*)(ws + WS_BT0), NTOK, N_IN0, DM};
;         pg8::StaticOrder S; S.init(NTOK, N_IN0, G, bid);
;         EpiIn E{0, ws};
;         for (int rep = 0; rep < NREP(1); ++rep) pg8::gemm_phase<EpiIn, pg8::StaticOrder, true, true>(lds, g, S, E);
.LBB0_372:
	s_or_b64 exec, exec, s[0:1]
	s_add_u32 s4, s50, 0x1180000
	s_addc_u32 s5, s51, 0
	v_mov_b32_e32 v0, 0
	global_load_dwordx4 v[4:7], v0, s[4:5] sc1
	global_load_dwordx4 v[8:11], v0, s[4:5] offset:16 sc1
	s_waitcnt vmcnt(0)
	v_bcnt_u32_b32 v4, v4, 0
	v_bcnt_u32_b32 v5, v5, 0
	v_bcnt_u32_b32 v6, v6, 0
	v_bcnt_u32_b32 v7, v7, 0
	v_bcnt_u32_b32 v8, v8, 0
	v_bcnt_u32_b32 v9, v9, 0
	v_bcnt_u32_b32 v10, v10, 0
	v_bcnt_u32_b32 v11, v11, 0
	v_xor_b32_e32 v4, 1, v4
	v_xor_b32_e32 v5, 1, v5
	v_xor_b32_e32 v6, 1, v6
	v_xor_b32_e32 v7, 1, v7
	v_xor_b32_e32 v8, 1, v8
	v_xor_b32_e32 v9, 1, v9
	v_xor_b32_e32 v10, 1, v10
	v_xor_b32_e32 v11, 1, v11
	v_or3_b32 v4, v4, v5, v6
	v_or3_b32 v7, v7, v8, v9
	v_or3_b32 v4, v4, v7, v10
	v_or_b32_e32 v4, v4, v11
	s_nop 0
	v_readfirstlane_b32 s98, v4
	s_cmpk_lt_i32 s3, 0x800
	s_cselect_b64 s[0:1], -1, 0
	v_mov_b32_e32 v8, v234
	s_waitcnt lgkmcnt(0)
	s_barrier
	s_and_b64 vcc, exec, s[0:1]
	v_readfirstlane_b32 s2, v8
	s_cbranch_vccz .LBB0_374
	s_ashr_i32 s4, s3, 31
	s_lshr_b32 s4, s4, 29
	s_add_i32 s4, s3, s4
	s_and_b32 s5, s4, -8
	s_sub_i32 s5, s3, s5
	s_lshl_b32 s7, s5, 8
	s_ashr_i32 s4, s4, 3
	s_mul_i32 s6, s5, 0x101
	s_cmp_lt_i32 s5, 0
	s_cselect_b32 s5, s6, s7
	s_add_i32 s4, s5, s4
	s_ashr_i32 s5, s4, 31
	s_lshr_b32 s5, s5, 25
	s_add_i32 s5, s4, s5
	s_ashr_i32 s6, s5, 7
	s_and_b32 s5, s5, 0xffffff80
	s_sub_i32 s4, s4, s5
	s_bfe_i32 s5, s4, 0x80000
	s_bfe_u32 s5, s5, 0x3000c
	s_add_i32 s5, s4, s5
	s_bfe_i32 s7, s5, 0x80000
	s_and_b32 s5, s5, 0xf8
	s_sub_i32 s4, s4, s5
	s_lshl_b32 s6, s6, 3
	s_sext_i32_i16 s7, s7
	s_sext_i32_i8 s4, s4
	s_add_i32 s10, s6, s4
	s_ashr_i32 s6, s7, 3

; __device__ __forceinline__ unsigned xb_ld(unsigned* p)              { return __hip_atomic_load(p, __ATOMIC_RELAXED, __HIP_MEMORY_SCOPE_AGENT); }
; __device__ __forceinline__ unsigned xb_add(unsigned* p, unsigned v) { return __hip_atomic_fetch_add(p, v, __ATOMIC_RELAXED, __HIP_MEMORY_SCOPE_AGENT); }
; #define XB_SPIN(cond, bar) do { unsigned _sp = 0; while (cond) { __builtin_amdgcn_s_sleep(1); \
;     if ((++_sp & 255u) == 0u) { if (xb_ld(&(bar)[XB_TMO])) break; if (_sp > XB_SPIN_CAP) { atomicAdd(&(bar)[XB_TMO], 1u); break; } } } } while (0)
; __device__ __forceinline__ void xcd_barrier(const XcdBarrier& b) {
;     ...
;         if (old + 1u == (gen + 1u) * nloc) {
;             __builtin_amdgcn_fence(__ATOMIC_RELEASE, "agent");
;             asm volatile("s_waitcnt vmcnt(0)" ::: "memory");
;             const unsigned og = xb_add(&bar[XB_TOP], 1u);
;             const unsigned tg = og / nx;
;             if (og + 1u == (tg + 1u) * nx) xb_add(&bar[XB_TOPGEN], 1u);
;             else XB_SPIN(xb_ld(&bar[XB_TOPGEN]) == tg, bar);
;             __builtin_amdgcn_fence(__ATOMIC_ACQUIRE, "agent");
;             xb_add(&bar[XB_XGEN(b.x)], 1u);
;             asm volatile("s_waitcnt vmcnt(0)" ::: "memory");
.LBB0_478:
	s_andn2_saveexec_b64 s[6:7], s[6:7]
	s_cbranch_execz .LBB0_498
	s_mov_b64 s[8:9], exec
	s_cmp_eq_u32 s98, 0
	s_cbranch_scc1 .LBB0_495
	buffer_wbl2 sc1
	s_waitcnt lgkmcnt(0)
	s_waitcnt vmcnt(0)
	v_mbcnt_lo_u32_b32 v1, s8, 0
	v_mbcnt_hi_u32_b32 v1, s9, v1
	v_cmp_eq_u32_e32 vcc, 0, v1
	s_and_saveexec_b64 s[10:11], vcc
	s_cbranch_execz .LBB0_481
	s_bcnt1_i32_b64 s2, s[8:9]
	v_mov_b32_e32 v2, 0x1183000
	v_mov_b32_e32 v3, s2
	global_atomic_add v2, v2, v3, s[50:51] offset:1024 sc0

; __device__ __forceinline__ unsigned xb_ld(unsigned* p)              { return __hip_atomic_load(p, __ATOMIC_RELAXED, __HIP_MEMORY_SCOPE_AGENT); }
; __device__ __forceinline__ unsigned xb_add(unsigned* p, unsigned v) { return __hip_atomic_fetch_add(p, v, __ATOMIC_RELAXED, __HIP_MEMORY_SCOPE_AGENT); }
; #define XB_SPIN(cond, bar) do { unsigned _sp = 0; while (cond) { __builtin_amdgcn_s_sleep(1); \
;     if ((++_sp & 255u) == 0u) { if (xb_ld(&(bar)[XB_TMO])) break; if (_sp > XB_SPIN_CAP) { atomicAdd(&(bar)[XB_TMO], 1u); break; } } } } while (0)
; __device__ __forceinline__ void xcd_barrier(const XcdBarrier& b) {
;     ...
;         if (old + 1u == (gen + 1u) * nloc) {
;             __builtin_amdgcn_fence(__ATOMIC_RELEASE, "agent");
;             asm volatile("s_waitcnt vmcnt(0)" ::: "memory");
;             const unsigned og = xb_add(&bar[XB_TOP], 1u);
;             const unsigned tg = og / nx;
;             if (og + 1u == (tg + 1u) * nx) xb_add(&bar[XB_TOPGEN], 1u);
;             else XB_SPIN(xb_ld(&bar[XB_TOPGEN]) == tg, bar);
;             __builtin_amdgcn_fence(__ATOMIC_ACQUIRE, "agent");
;             xb_add(&bar[XB_XGEN(b.x)], 1u);
;             asm volatile("s_waitcnt vmcnt(0)" ::: "memory");
.LBB0_714:
	s_andn2_saveexec_b64 s[8:9], s[8:9]
	s_cbranch_execz .LBB0_734
	s_mov_b64 s[10:11], exec
	s_cmp_eq_u32 s98, 0
	s_cbranch_scc1 .LBB0_731
	buffer_wbl2 sc1
	s_waitcnt lgkmcnt(0)
	s_waitcnt vmcnt(0)
	v_mbcnt_lo_u32_b32 v1, s10, 0
	v_mbcnt_hi_u32_b32 v1, s11, v1
	v_cmp_eq_u32_e32 vcc, 0, v1
	s_and_saveexec_b64 s[12:13], vcc
	s_cbranch_execz .LBB0_717
	s_bcnt1_i32_b64 s0, s[10:11]
	v_mov_b32_e32 v2, 0x1183000
	v_mov_b32_e32 v3, s0
	global_atomic_add v2, v2, v3, s[50:51] offset:1024 sc0

; __device__ __forceinline__ unsigned xb_ld(unsigned* p)              { return __hip_atomic_load(p, __ATOMIC_RELAXED, __HIP_MEMORY_SCOPE_AGENT); }
; __device__ __forceinline__ unsigned xb_add(unsigned* p, unsigned v) { return __hip_atomic_fetch_add(p, v, __ATOMIC_RELAXED, __HIP_MEMORY_SCOPE_AGENT); }
; #define XB_SPIN(cond, bar) do { unsigned _sp = 0; while (cond) { __builtin_amdgcn_s_sleep(1); \
;     if ((++_sp & 255u) == 0u) { if (xb_ld(&(bar)[XB_TMO])) break; if (_sp > XB_SPIN_CAP) { atomicAdd(&(bar)[XB_TMO], 1u); break; } } } } while (0)
; __device__ __forceinline__ void xcd_barrier(const XcdBarrier& b) {
;     ...
;         if (old + 1u == (gen + 1u) * nloc) {
;             __builtin_amdgcn_fence(__ATOMIC_RELEASE, "agent");
;             asm volatile("s_waitcnt vmcnt(0)" ::: "memory");
;             const unsigned og = xb_add(&bar[XB_TOP], 1u);
;             const unsigned tg = og / nx;
;             if (og + 1u == (tg + 1u) * nx) xb_add(&bar[XB_TOPGEN], 1u);
;             else XB_SPIN(xb_ld(&bar[XB_TOPGEN]) == tg, bar);
;             __builtin_amdgcn_fence(__ATOMIC_ACQUIRE, "agent");
;             xb_add(&bar[XB_XGEN(b.x)], 1u);
;             asm volatile("s_waitcnt vmcnt(0)" ::: "memory");
.LBB0_805:
	s_andn2_saveexec_b64 s[8:9], s[8:9]
	s_cbranch_execz .LBB0_825
	s_mov_b64 s[10:11], exec
	s_cmp_eq_u32 s98, 0
	s_cbranch_scc1 .LBB0_822
	buffer_wbl2 sc1
	s_waitcnt lgkmcnt(0)
	s_waitcnt vmcnt(0)
	v_mbcnt_lo_u32_b32 v1, s10, 0
	v_mbcnt_hi_u32_b32 v1, s11, v1
	v_cmp_eq_u32_e32 vcc, 0, v1
	s_and_saveexec_b64 s[12:13], vcc
	s_cbranch_execz .LBB0_808
	s_bcnt1_i32_b64 s2, s[10:11]
	v_mov_b32_e32 v2, 0x1183000
	v_mov_b32_e32 v3, s2
	global_atomic_add v2, v2, v3, s[50:51] offset:1024 sc0

; __device__ __forceinline__ unsigned xb_ld(unsigned* p)              { return __hip_atomic_load(p, __ATOMIC_RELAXED, __HIP_MEMORY_SCOPE_AGENT); }
; __device__ __forceinline__ unsigned xb_add(unsigned* p, unsigned v) { return __hip_atomic_fetch_add(p, v, __ATOMIC_RELAXED, __HIP_MEMORY_SCOPE_AGENT); }
; #define XB_SPIN(cond, bar) do { unsigned _sp = 0; while (cond) { __builtin_amdgcn_s_sleep(1); \
;     if ((++_sp & 255u) == 0u) { if (xb_ld(&(bar)[XB_TMO])) break; if (_sp > XB_SPIN_CAP) { atomicAdd(&(bar)[XB_TMO], 1u); break; } } } } while (0)
; __device__ __forceinline__ void xcd_barrier(const XcdBarrier& b) {
;     ...
;         if (old + 1u == (gen + 1u) * nloc) {
;             __builtin_amdgcn_fence(__ATOMIC_RELEASE, "agent");
;             asm volatile("s_waitcnt vmcnt(0)" ::: "memory");
;             const unsigned og = xb_add(&bar[XB_TOP], 1u);
;             const unsigned tg = og / nx;
;             if (og + 1u == (tg + 1u) * nx) xb_add(&bar[XB_TOPGEN], 1u);
;             else XB_SPIN(xb_ld(&bar[XB_TOPGEN]) == tg, bar);
;             __builtin_amdgcn_fence(__ATOMIC_ACQUIRE, "agent");
;             xb_add(&bar[XB_XGEN(b.x)], 1u);
;             asm volatile("s_waitcnt vmcnt(0)" ::: "memory");
.LBB0_887:
	s_andn2_saveexec_b64 s[6:7], s[6:7]
	s_cbranch_execz .LBB0_907
	s_mov_b64 s[8:9], exec
	s_cmp_eq_u32 s98, 0
	s_cbranch_scc1 .LBB0_904
	buffer_wbl2 sc1
	s_waitcnt lgkmcnt(0)
	s_waitcnt vmcnt(0)
	v_mbcnt_lo_u32_b32 v1, s8, 0
	v_mbcnt_hi_u32_b32 v1, s9, v1
	v_cmp_eq_u32_e32 vcc, 0, v1
	s_and_saveexec_b64 s[12:13], vcc
	s_cbranch_execz .LBB0_890
	s_bcnt1_i32_b64 s2, s[8:9]
	v_mov_b32_e32 v2, 0x1183000
	v_mov_b32_e32 v3, s2
	global_atomic_add v2, v2, v3, s[50:51] offset:1024 sc0

; __device__ __forceinline__ unsigned xb_ld(unsigned* p)              { return __hip_atomic_load(p, __ATOMIC_RELAXED, __HIP_MEMORY_SCOPE_AGENT); }
; __device__ __forceinline__ unsigned xb_add(unsigned* p, unsigned v) { return __hip_atomic_fetch_add(p, v, __ATOMIC_RELAXED, __HIP_MEMORY_SCOPE_AGENT); }
; #define XB_SPIN(cond, bar) do { unsigned _sp = 0; while (cond) { __builtin_amdgcn_s_sleep(1); \
;     if ((++_sp & 255u) == 0u) { if (xb_ld(&(bar)[XB_TMO])) break; if (_sp > XB_SPIN_CAP) { atomicAdd(&(bar)[XB_TMO], 1u); break; } } } } while (0)
; __device__ __forceinline__ void xcd_barrier(const XcdBarrier& b) {
;     ...
;         if (old + 1u == (gen + 1u) * nloc) {
;             __builtin_amdgcn_fence(__ATOMIC_RELEASE, "agent");
;             asm volatile("s_waitcnt vmcnt(0)" ::: "memory");
;             const unsigned og = xb_add(&bar[XB_TOP], 1u);
;             const unsigned tg = og / nx;
;             if (og + 1u == (tg + 1u) * nx) xb_add(&bar[XB_TOPGEN], 1u);
;             else XB_SPIN(xb_ld(&bar[XB_TOPGEN]) == tg, bar);
;             __builtin_amdgcn_fence(__ATOMIC_ACQUIRE, "agent");
;             xb_add(&bar[XB_XGEN(b.x)], 1u);
;             asm volatile("s_waitcnt vmcnt(0)" ::: "memory");
.LBB0_960:
	s_andn2_saveexec_b64 s[6:7], s[6:7]
	s_cbranch_execz .LBB0_980
	s_mov_b64 s[6:7], exec
	s_cmp_eq_u32 s98, 0
	s_cbranch_scc1 .LBB0_977
	buffer_wbl2 sc1
	s_waitcnt lgkmcnt(0)
	s_waitcnt vmcnt(0)
	v_mbcnt_lo_u32_b32 v1, s6, 0
	v_mbcnt_hi_u32_b32 v1, s7, v1
	v_cmp_eq_u32_e32 vcc, 0, v1
	s_and_saveexec_b64 s[8:9], vcc
	s_cbranch_execz .LBB0_963
	s_bcnt1_i32_b64 s2, s[6:7]
	v_mov_b32_e32 v2, 0x1183000
	v_mov_b32_e32 v3, s2
	global_atomic_add v2, v2, v3, s[50:51] offset:1024 sc0

; __global__ void __launch_bounds__(NTHREADS) fwd_megakernel(Params P) {
	.amdhsa_kernel _Z14fwd_megakernel6Params
		.amdhsa_group_segment_fixed_size 0
		.amdhsa_private_segment_fixed_size 0
		.amdhsa_kernarg_size 384
		.amdhsa_user_sgpr_count 2
		.amdhsa_user_sgpr_dispatch_ptr 0
		.amdhsa_user_sgpr_queue_ptr 0
		.amdhsa_user_sgpr_kernarg_segment_ptr 1
		.amdhsa_user_sgpr_dispatch_id 0
		.amdhsa_user_sgpr_kernarg_preload_length 0
		.amdhsa_user_sgpr_kernarg_preload_offset 0
		.amdhsa_user_sgpr_private_segment_size 0
		.amdhsa_uses_dynamic_stack 0
		.amdhsa_enable_private_segment 0
		.amdhsa_system_sgpr_workgroup_id_x 1
		.amdhsa_system_sgpr_workgroup_id_y 0
		.amdhsa_system_sgpr_workgroup_id_z 0
		.amdhsa_system_sgpr_workgroup_info 0
		.amdhsa_system_vgpr_workitem_id 2
		.amdhsa_next_free_vgpr 256
		.amdhsa_next_free_sgpr 100
		.amdhsa_accum_offset 256
		.amdhsa_reserve_vcc 1
		.amdhsa_float_round_mode_32 0
		.amdhsa_float_round_mode_16_64 0
		.amdhsa_float_denorm_mode_32 3
		.amdhsa_float_denorm_mode_16_64 3
		.amdhsa_dx10_clamp 1
		.amdhsa_ieee_mode 1
		.amdhsa_fp16_overflow 0
		.amdhsa_tg_split 0
		.amdhsa_exception_fp_ieee_invalid_op 0
		.amdhsa_exception_fp_denorm_src 0
		.amdhsa_exception_fp_ieee_div_zero 0
		.amdhsa_exception_fp_ieee_overflow 0
		.amdhsa_exception_fp_ieee_underflow 0
		.amdhsa_exception_fp_ieee_inexact 0
		.amdhsa_exception_int_div_zero 0
	.end_amdhsa_kernel

; __global__ void __launch_bounds__(NTHREADS) fwd_megakernel(Params P) {
amdhsa.kernels:
  - .agpr_count:     0
    .args:
      - .offset:         0
        .size:           128
        .value_kind:     by_value
      - .offset:         128
        .size:           4
        .value_kind:     hidden_block_count_x
      - .offset:         132
        .size:           4
        .value_kind:     hidden_block_count_y
      - .offset:         136
        .size:           4
        .value_kind:     hidden_block_count_z
      - .offset:         140
        .size:           2
        .value_kind:     hidden_group_size_x
      - .offset:         142
        .size:           2
        .value_kind:     hidden_group_size_y
      - .offset:         144
        .size:           2
        .value_kind:     hidden_group_size_z
      - .offset:         146
        .size:           2
        .value_kind:     hidden_remainder_x
      - .offset:         148
        .size:           2
        .value_kind:     hidden_remainder_y
      - .offset:         150
        .size:           2
        .value_kind:     hidden_remainder_z
      - .offset:         168
        .size:           8
        .value_kind:     hidden_global_offset_x
      - .offset:         176
        .size:           8
        .value_kind:     hidden_global_offset_y
      - .offset:         184
        .size:           8
        .value_kind:     hidden_global_offset_z
      - .offset:         192
        .size:           2
        .value_kind:     hidden_grid_dims
      - .offset:         216
        .size:           8
        .value_kind:     hidden_multigrid_sync_arg
      - .offset:         248
        .size:           4
        .value_kind:     hidden_dynamic_lds_size
    .group_segment_fixed_size: 0
    .kernarg_segment_align: 8
    .kernarg_segment_size: 384
    .language:       OpenCL C
    .language_version:
      - 2
      - 0
    .max_flat_workgroup_size: 512
    .name:           _Z14fwd_megakernel6Params
    .private_segment_fixed_size: 0
    .sgpr_count:     106
    .sgpr_spill_count: 16
    .symbol:         _Z14fwd_megakernel6Params.kd
    .uniform_work_group_size: 1
    .uses_dynamic_stack: false
    .vgpr_count:     256
    .vgpr_spill_count: 0
    .wavefront_size: 64
